# phase 0 W_uq / W_ukv transpose tiles: 16 weight loads and 16 gain loads issued back to back with one wait instead of a wait per element
# baseline (speedup 1.0000x reference)
; DI bf16_t f2bf(float a) { return (bf16_t)(pk2(a, 0.f) & 0xffffu); }
; template <int MODE>
; DI void transpose_tile(const float* __restrict__ W, int K, int Nsrc, bf16_t* __restrict__ WT, int ldo, const float* __restrict__ gain, int k0, int n0,
;                        unsigned char* smem, int tid) {
;     ...
; #pragma unroll 4
;     for (int i = 0; i < 16; ++i) {
;         const int e = tid + 256 * i, kk = e >> 6, nn = e & 63;
;         const int src = MODE == 0 ? win_src_col(n0 + nn) : (n0 + nn);
;         float v = src >= 0 ? W[(size_t)(k0 + kk) * Nsrc + src] : 0.f;
;         if (gain) v *= gain[k0 + kk];
;         t[nn * 66 + kk] = f2bf(v);
;     }
; DI void phase0(const Params& p, unsigned char* smem) {
;     ...
;         if (r < T_UKV) { transpose_tile<1>(p.w_ukv, 256, 2048, (bf16_t*)(p.ws + WS_WUKV), 256, p.kv_a_gain, (r / 32) * 64, (r % 32) * 64, smem, tid); continue; }
.LBB0_35:
	s_and_b64 vcc, exec, s[0:1]
	s_cbranch_vccz .LBB0_47
	v_and_b32_e32 v1, 63, v6
	v_or_b32_e32 v3, s4, v1
	s_add_i32 s5, s5, 0x7fffe680
	v_lshlrev_b32_e32 v4, 2, v3
	v_mov_b32_e32 v3, s10
	s_and_b32 s5, s5, 0x7fffffc0
	v_lshl_add_u64 v[8:9], s[54:55], 0, v[4:5]
	v_mad_u32_u24 v1, v1, s27, v3
	v_lshrrev_b32_e32 v3, 6, v6
	v_add_u32_e32 v10, s5, v3
	v_ashrrev_i32_e32 v11, 31, v10
	v_lshlrev_b64 v[12:13], 13, v[10:11]
	v_lshl_add_u64 v[12:13], v[8:9], 0, v[12:13]
	v_lshl_add_u32 v1, v3, 1, v1
	v_lshl_add_u64 v[10:11], v[10:11], 2, s[50:51]
	s_mov_b32 s0, 0x8000
	s_mov_b32 s1, 0
	global_load_dword v14, v[12:13], off
	v_lshl_add_u64 v[12:13], v[12:13], 0, s[0:1]
	global_load_dword v15, v[12:13], off
	v_lshl_add_u64 v[12:13], v[12:13], 0, s[0:1]
	global_load_dword v16, v[12:13], off
	v_lshl_add_u64 v[12:13], v[12:13], 0, s[0:1]
	global_load_dword v17, v[12:13], off
	v_lshl_add_u64 v[12:13], v[12:13], 0, s[0:1]
	global_load_dword v18, v[12:13], off
	v_lshl_add_u64 v[12:13], v[12:13], 0, s[0:1]
	global_load_dword v19, v[12:13], off
	v_lshl_add_u64 v[12:13], v[12:13], 0, s[0:1]
	global_load_dword v20, v[12:13], off
	v_lshl_add_u64 v[12:13], v[12:13], 0, s[0:1]
	global_load_dword v21, v[12:13], off
	v_lshl_add_u64 v[12:13], v[12:13], 0, s[0:1]
	global_load_dword v22, v[12:13], off
	v_lshl_add_u64 v[12:13], v[12:13], 0, s[0:1]
	global_load_dword v23, v[12:13], off
	v_lshl_add_u64 v[12:13], v[12:13], 0, s[0:1]
	global_load_dword v24, v[12:13], off
	v_lshl_add_u64 v[12:13], v[12:13], 0, s[0:1]
	global_load_dword v25, v[12:13], off
	v_lshl_add_u64 v[12:13], v[12:13], 0, s[0:1]
	global_load_dword v26, v[12:13], off
	v_lshl_add_u64 v[12:13], v[12:13], 0, s[0:1]
	global_load_dword v27, v[12:13], off
	v_lshl_add_u64 v[12:13], v[12:13], 0, s[0:1]
	global_load_dword v28, v[12:13], off
	v_lshl_add_u64 v[12:13], v[12:13], 0, s[0:1]
	global_load_dword v29, v[12:13], off
	v_mov_b32_e32 v38, 1.0
	v_mov_b32_e32 v39, 1.0
	v_mov_b32_e32 v40, 1.0
	v_mov_b32_e32 v41, 1.0
	v_mov_b32_e32 v42, 1.0
	v_mov_b32_e32 v43, 1.0
	v_mov_b32_e32 v44, 1.0
	v_mov_b32_e32 v45, 1.0
	v_mov_b32_e32 v46, 1.0
	v_mov_b32_e32 v47, 1.0
	v_mov_b32_e32 v48, 1.0
	v_mov_b32_e32 v49, 1.0
	v_mov_b32_e32 v50, 1.0
	v_mov_b32_e32 v51, 1.0
	v_mov_b32_e32 v52, 1.0
	v_mov_b32_e32 v53, 1.0
	s_andn2_b64 vcc, exec, s[16:17]
	s_cbranch_vccnz .Lwt_ukv_nogain
	global_load_dword v38, v[10:11], off
	global_load_dword v39, v[10:11], off offset:16
	global_load_dword v40, v[10:11], off offset:32
	global_load_dword v41, v[10:11], off offset:48
	global_load_dword v42, v[10:11], off offset:64
	global_load_dword v43, v[10:11], off offset:80
	global_load_dword v44, v[10:11], off offset:96
	global_load_dword v45, v[10:11], off offset:112
	global_load_dword v46, v[10:11], off offset:128
	global_load_dword v47, v[10:11], off offset:144
	global_load_dword v48, v[10:11], off offset:160
	global_load_dword v49, v[10:11], off offset:176
	global_load_dword v50, v[10:11], off offset:192
	global_load_dword v51, v[10:11], off offset:208
	global_load_dword v52, v[10:11], off offset:224
	global_load_dword v53, v[10:11], off offset:240
.Lwt_ukv_nogain:
	s_waitcnt vmcnt(0)
	v_mul_f32_e32 v14, v14, v38
	v_mul_f32_e32 v15, v15, v39
	v_mul_f32_e32 v16, v16, v40
	v_mul_f32_e32 v17, v17, v41
	v_mul_f32_e32 v18, v18, v42
	v_mul_f32_e32 v19, v19, v43
	v_mul_f32_e32 v20, v20, v44
	v_mul_f32_e32 v21, v21, v45
	v_mul_f32_e32 v22, v22, v46
	v_mul_f32_e32 v23, v23, v47
	v_mul_f32_e32 v24, v24, v48
	v_mul_f32_e32 v25, v25, v49
	v_mul_f32_e32 v26, v26, v50
	v_mul_f32_e32 v27, v27, v51
	v_mul_f32_e32 v28, v28, v52
	v_mul_f32_e32 v29, v29, v53
	v_cvt_pk_bf16_f32 v14, v14, v15
	ds_write_b16 v1, v14
	ds_write_b16_d16_hi v1, v14 offset:8
	v_cvt_pk_bf16_f32 v16, v16, v17
	ds_write_b16 v1, v16 offset:16
	ds_write_b16_d16_hi v1, v16 offset:24
	v_cvt_pk_bf16_f32 v18, v18, v19
	ds_write_b16 v1, v18 offset:32
	ds_write_b16_d16_hi v1, v18 offset:40
	v_cvt_pk_bf16_f32 v20, v20, v21
	ds_write_b16 v1, v20 offset:48
	ds_write_b16_d16_hi v1, v20 offset:56
	v_cvt_pk_bf16_f32 v22, v22, v23
	ds_write_b16 v1, v22 offset:64
	ds_write_b16_d16_hi v1, v22 offset:72
	v_cvt_pk_bf16_f32 v24, v24, v25
	ds_write_b16 v1, v24 offset:80
	ds_write_b16_d16_hi v1, v24 offset:88
	v_cvt_pk_bf16_f32 v26, v26, v27
	ds_write_b16 v1, v26 offset:96
	ds_write_b16_d16_hi v1, v26 offset:104
	v_cvt_pk_bf16_f32 v28, v28, v29
	ds_write_b16 v1, v28 offset:112
	ds_write_b16_d16_hi v1, v28 offset:120

; DI bf16_t f2bf(float a) { return (bf16_t)(pk2(a, 0.f) & 0xffffu); }
; template <int MODE>
; DI void transpose_tile(const float* __restrict__ W, int K, int Nsrc, bf16_t* __restrict__ WT, int ldo, const float* __restrict__ gain, int k0, int n0,
;                        unsigned char* smem, int tid) {
;     ...
; #pragma unroll 4
;     for (int i = 0; i < 16; ++i) {
;         const int e = tid + 256 * i, kk = e >> 6, nn = e & 63;
;         const int src = MODE == 0 ? win_src_col(n0 + nn) : (n0 + nn);
;         float v = src >= 0 ? W[(size_t)(k0 + kk) * Nsrc + src] : 0.f;
;         if (gain) v *= gain[k0 + kk];
;         t[nn * 66 + kk] = f2bf(v);
;     }
; DI void phase0(const Params& p, unsigned char* smem) {
;     ...
;         if (r < T_UQ) { transpose_tile<1>(p.w_uq, 512, 1536, (bf16_t*)(p.ws + WS_WUQ), 512, p.q_a_gain, (r / 24) * 64, (r % 24) * 64, smem, tid); continue; }
.LBB0_48:
	s_andn2_b64 vcc, exec, s[0:1]
	s_cbranch_vccnz .LBB0_60
	s_and_b32 s0, s35, 0xff
	s_mulk_i32 s0, 0xab
	s_lshr_b32 s0, s0, 12
	s_lshl_b32 s5, s0, 6
	s_mul_i32 s0, s0, 24
	s_sub_i32 s0, s35, s0
	s_and_b32 s0, s0, 0xff
	s_lshl_b32 s4, s0, 6
	v_and_b32_e32 v1, 63, v6
	v_or_b32_e32 v3, s4, v1
	v_lshlrev_b32_e32 v4, 2, v3
	v_mov_b32_e32 v3, s10
	v_lshl_add_u64 v[8:9], s[52:53], 0, v[4:5]
	v_mad_u32_u24 v1, v1, s27, v3
	v_lshrrev_b32_e32 v3, 6, v6
	v_add_u32_e32 v10, s5, v3
	v_mad_i64_i32 v[12:13], s[6:7], v10, s29, v[8:9]
	v_ashrrev_i32_e32 v11, 31, v10
	v_lshl_add_u32 v1, v3, 1, v1
	v_lshl_add_u64 v[10:11], v[10:11], 2, s[48:49]
	s_mov_b32 s0, 0x6000
	s_mov_b32 s1, 0
	global_load_dword v14, v[12:13], off
	v_lshl_add_u64 v[12:13], v[12:13], 0, s[0:1]
	global_load_dword v15, v[12:13], off
	v_lshl_add_u64 v[12:13], v[12:13], 0, s[0:1]
	global_load_dword v16, v[12:13], off
	v_lshl_add_u64 v[12:13], v[12:13], 0, s[0:1]
	global_load_dword v17, v[12:13], off
	v_lshl_add_u64 v[12:13], v[12:13], 0, s[0:1]
	global_load_dword v18, v[12:13], off
	v_lshl_add_u64 v[12:13], v[12:13], 0, s[0:1]
	global_load_dword v19, v[12:13], off
	v_lshl_add_u64 v[12:13], v[12:13], 0, s[0:1]
	global_load_dword v20, v[12:13], off
	v_lshl_add_u64 v[12:13], v[12:13], 0, s[0:1]
	global_load_dword v21, v[12:13], off
	v_lshl_add_u64 v[12:13], v[12:13], 0, s[0:1]
	global_load_dword v22, v[12:13], off
	v_lshl_add_u64 v[12:13], v[12:13], 0, s[0:1]
	global_load_dword v23, v[12:13], off
	v_lshl_add_u64 v[12:13], v[12:13], 0, s[0:1]
	global_load_dword v24, v[12:13], off
	v_lshl_add_u64 v[12:13], v[12:13], 0, s[0:1]
	global_load_dword v25, v[12:13], off
	v_lshl_add_u64 v[12:13], v[12:13], 0, s[0:1]
	global_load_dword v26, v[12:13], off
	v_lshl_add_u64 v[12:13], v[12:13], 0, s[0:1]
	global_load_dword v27, v[12:13], off
	v_lshl_add_u64 v[12:13], v[12:13], 0, s[0:1]
	global_load_dword v28, v[12:13], off
	v_lshl_add_u64 v[12:13], v[12:13], 0, s[0:1]
	global_load_dword v29, v[12:13], off
	v_mov_b32_e32 v38, 1.0
	v_mov_b32_e32 v39, 1.0
	v_mov_b32_e32 v40, 1.0
	v_mov_b32_e32 v41, 1.0
	v_mov_b32_e32 v42, 1.0
	v_mov_b32_e32 v43, 1.0
	v_mov_b32_e32 v44, 1.0
	v_mov_b32_e32 v45, 1.0
	v_mov_b32_e32 v46, 1.0
	v_mov_b32_e32 v47, 1.0
	v_mov_b32_e32 v48, 1.0
	v_mov_b32_e32 v49, 1.0
	v_mov_b32_e32 v50, 1.0
	v_mov_b32_e32 v51, 1.0
	v_mov_b32_e32 v52, 1.0
	v_mov_b32_e32 v53, 1.0
	s_andn2_b64 vcc, exec, s[18:19]
	s_cbranch_vccnz .Lwt_uq_nogain
	global_load_dword v38, v[10:11], off
	global_load_dword v39, v[10:11], off offset:16
	global_load_dword v40, v[10:11], off offset:32
	global_load_dword v41, v[10:11], off offset:48
	global_load_dword v42, v[10:11], off offset:64
	global_load_dword v43, v[10:11], off offset:80
	global_load_dword v44, v[10:11], off offset:96
	global_load_dword v45, v[10:11], off offset:112
	global_load_dword v46, v[10:11], off offset:128
	global_load_dword v47, v[10:11], off offset:144
	global_load_dword v48, v[10:11], off offset:160
	global_load_dword v49, v[10:11], off offset:176
	global_load_dword v50, v[10:11], off offset:192
	global_load_dword v51, v[10:11], off offset:208
	global_load_dword v52, v[10:11], off offset:224
	global_load_dword v53, v[10:11], off offset:240
